# s5_b LDS staging: the seven HT table loads issued together with counted waits instead of one round trip each, on top of v13
# baseline (speedup 1.0000x reference)
; #define LAS __attribute__((address_space(3)))
; DI void s5_b_lds(const Prm& p, LAS unsigned char* lds, int tid, int lane, int wave) {
;     ...
;     for (int gp = blockIdx.x; gp < 256; gp += gridDim.x) { const int g = gp & 31, part = gp >> 5;
;         for (int i = tid; i < 128 * 32; i += 512) { const int row = i >> 5, ch = i & 31;
;             *(LAS u32x4v*)(lds + row * 528 + ch * 16) = *(const u32x4v*)(p.HT + ((size_t)(g * 128 + row)) * 256 + ch * 8); }
;         __syncthreads();
.LBB0_774:
	s_and_b32 s2, s19, 31
	s_lshl_b32 s3, s2, 15
	v_or_b32_e32 v0, s3, v65
	v_lshlrev_b32_e32 v36, 1, v0
	v_lshl_add_u64 v[192:193], v[38:39], 0, v[36:37]
	global_load_dwordx4 v[192:195], v[192:193], off
	v_or_b32_e32 v0, s3, v66
	v_lshlrev_b32_e32 v36, 1, v0
	v_lshl_add_u64 v[196:197], v[38:39], 0, v[36:37]
	global_load_dwordx4 v[196:199], v[196:197], off
	v_or_b32_e32 v0, s3, v67
	v_lshlrev_b32_e32 v36, 1, v0
	v_lshl_add_u64 v[200:201], v[38:39], 0, v[36:37]
	global_load_dwordx4 v[200:203], v[200:201], off
	v_or_b32_e32 v0, s3, v68
	v_lshlrev_b32_e32 v36, 1, v0
	v_lshl_add_u64 v[204:205], v[38:39], 0, v[36:37]
	global_load_dwordx4 v[204:207], v[204:205], off
	v_or_b32_e32 v0, s3, v69
	v_lshlrev_b32_e32 v36, 1, v0
	v_lshl_add_u64 v[208:209], v[38:39], 0, v[36:37]
	global_load_dwordx4 v[208:211], v[208:209], off
	v_or_b32_e32 v0, s3, v70
	v_lshlrev_b32_e32 v36, 1, v0
	v_lshl_add_u64 v[212:213], v[38:39], 0, v[36:37]
	global_load_dwordx4 v[212:215], v[212:213], off
	v_or_b32_e32 v0, s3, v71
	v_lshlrev_b32_e32 v36, 1, v0
	v_lshl_add_u64 v[216:217], v[38:39], 0, v[36:37]
	global_load_dwordx4 v[216:219], v[216:217], off
	s_waitcnt vmcnt(6)
	ds_write_b128 v78, v[192:195]
	s_waitcnt vmcnt(5)
	ds_write_b128 v79, v[196:199]
	s_waitcnt vmcnt(4)
	ds_write_b128 v78, v[200:203] offset:16896
	s_waitcnt vmcnt(3)
	ds_write_b128 v80, v[204:207]
	s_waitcnt vmcnt(2)
	ds_write_b128 v78, v[208:211] offset:33792
	s_waitcnt vmcnt(1)
	ds_write_b128 v81, v[212:215]
	s_waitcnt vmcnt(0)
	ds_write_b128 v82, v[216:219]
	s_and_saveexec_b64 s[0:1], vcc
	s_cbranch_execz .LBB0_776
	v_add_lshl_u32 v36, v72, s3, 1
	v_lshl_add_u64 v[0:1], v[38:39], 0, v[36:37]
	global_load_dwordx4 v[0:3], v[0:1], off
	s_waitcnt vmcnt(0)
	ds_write_b128 v83, v[0:3]
